# speedup vs baseline: 1.0077x; 1.0077x over previous
; template <class LA>
; DI void gemm_tile(const LA& la, int m0, const u16* __restrict__ Bm, long ldb, int K, f32x16 (&acc)[2][2], char* lds, int tid) {
;     ...
;   const int nk = K >> 6;
;   const u16* bp = Bm + (long)lr * ldb + lc;
;   const long b32 = 32 * ldb;
;     ...
;   const int arow = (wm * 64 + (lane & 31)) * 144 + (lane >> 5) * 16;
;   const int brow = 18432 + (wn * 64 + (lane & 31)) * 144 + (lane >> 5) * 16;
;   char* lds0 = lds;
;   char* lds1 = lds + 36864;
;   __syncthreads();
;   GT_LOAD(p, 0)
;   if (nk > 1) { GT_LOAD(q, 64) }
;   GT_STORE(p, lds0)
;   __syncthreads();
; template <int MASK>
; __global__ void __launch_bounds__(256, 2) fwd_megakernel_t(Params p) {
;     ...
;         for (int br = 0; br < 3; br++) {
;           const u16* Ap = (br == 0) ? osb : (br == 1) ? odil : omla;
;           const int Kb = (br == 0) ? 512 : (br == 1) ? 256 : 768;
;           const u16* Bp = ((br == 0) ? w_bsb : (br == 1) ? w_bdil : w_bmla) + (size_t)n0 * Kb;
;           gemm_tile(LoadPlain{Ap, Kb}, m0, Bp, Kb, Kb, acc, lds, tid);
.LBB0_399:
	s_cmp_eq_u32 s14, 1
	s_movk_i32 s7, 0x300
	s_mov_b32 s8, 0x2e60000
	s_cselect_b32 s5, s94, s85
	s_cselect_b32 s6, s95, s1
	s_cselect_b32 s7, 0x100, s7
	s_cselect_b32 s15, s8, 0x2f60000
	s_cmp_eq_u32 s14, 0
	s_cselect_b32 s8, s91, s5
	s_cselect_b32 s20, 0x200, s7
	s_cselect_b32 s5, 0x2c60000, s15
	s_cselect_b32 s9, s84, s6
	s_add_u32 s6, s88, s5
	s_mul_hi_i32 s17, s20, s4
	s_mul_i32 s16, s20, s4
	s_addc_u32 s7, s89, 0
	s_lshl_b64 s[16:17], s[16:17], 1
	s_add_u32 s16, s6, s16
	s_addc_u32 s17, s7, s17
	v_mad_i64_i32 v[64:65], s[18:19], s20, v128, 0
	v_lshl_add_u64 v[162:163], v[64:65], 1, s[16:17]
	s_waitcnt vmcnt(62)
	v_lshl_add_u64 v[112:113], v[162:163], 0, v[150:151]
	v_mad_i64_i32 v[64:65], s[16:17], s20, v140, 0
	v_mad_i64_i32 v[68:69], s[16:17], s20, v142, 0
	v_mad_i64_i32 v[72:73], s[16:17], s20, v144, 0
	v_mad_i64_i32 v[78:79], s[16:17], s20, v146, 0
	s_lshl_b32 s50, s20, 6
	v_lshl_add_u64 v[164:165], v[64:65], 1, s[8:9]
	v_lshl_add_u64 v[166:167], v[68:69], 1, s[8:9]
	v_lshl_add_u64 v[168:169], v[72:73], 1, s[8:9]
	v_lshl_add_u64 v[170:171], v[78:79], 1, s[8:9]
	v_lshl_add_u64 v[114:115], v[112:113], 0, s[50:51]
	v_lshl_add_u64 v[76:77], v[164:165], 0, v[150:151]
	v_lshl_add_u64 v[84:85], v[166:167], 0, v[150:151]
	v_lshl_add_u64 v[100:101], v[168:169], 0, v[150:151]
	v_lshl_add_u64 v[108:109], v[170:171], 0, v[150:151]
	v_lshl_add_u64 v[116:117], v[114:115], 0, s[50:51]
	s_barrier
	global_load_dwordx4 v[64:67], v[76:77], off
	global_load_dwordx4 v[68:71], v[84:85], off
	global_load_dwordx4 v[72:75], v[100:101], off
	global_load_dwordx4 v[80:83], v[108:109], off
	global_load_dwordx4 v[88:91], v[112:113], off
	global_load_dwordx4 v[92:95], v[114:115], off
	global_load_dwordx4 v[96:99], v[116:117], off
	v_lshl_add_u64 v[124:125], v[116:117], 0, s[50:51]
	global_load_dwordx4 v[104:107], v[124:125], off
	s_nop 0
	global_load_dwordx4 v[76:79], v[76:77], off offset:128
	s_nop 0
	global_load_dwordx4 v[84:87], v[84:85], off offset:128
	s_nop 0
	global_load_dwordx4 v[100:103], v[100:101], off offset:128
	s_nop 0
	global_load_dwordx4 v[108:111], v[108:109], off offset:128
	s_nop 0
	global_load_dwordx4 v[120:123], v[116:117], off offset:128
	s_nop 0
	global_load_dwordx4 v[116:119], v[114:115], off offset:128
	s_nop 0
	global_load_dwordx4 v[112:115], v[112:113], off offset:128
	s_nop 0
	global_load_dwordx4 v[124:127], v[124:125], off offset:128
	v_mov_b64_e32 v[176:177], s[6:7]
	v_mad_u64_u32 v[172:173], s[6:7], v156, s20, v[176:177]
	v_mad_u64_u32 v[174:175], s[6:7], v158, s20, v[176:177]
	v_mad_u64_u32 v[176:177], s[6:7], v160, s20, v[176:177]
	v_add_u32_e32 v208, v141, v143
	s_lshr_b32 s5, s20, 6
	v_mad_i32_i24 v173, v157, s20, v173
	v_mad_i32_i24 v175, v159, s20, v175
	v_mad_i32_i24 v177, v161, s20, v177
	s_mov_b32 s15, 3
	s_waitcnt vmcnt(15)
	ds_write_b128 v208, v[64:67]
	s_waitcnt vmcnt(14)
	ds_write_b128 v208, v[68:71] offset:4608
	s_waitcnt vmcnt(13)
	ds_write_b128 v208, v[72:75] offset:9216
	s_waitcnt vmcnt(12)
	ds_write_b128 v208, v[80:83] offset:13824
	s_waitcnt vmcnt(11)
	ds_write_b128 v208, v[88:91] offset:18432
	s_waitcnt vmcnt(10)
	ds_write_b128 v208, v[92:95] offset:23040
	s_waitcnt vmcnt(9)
	ds_write_b128 v208, v[96:99] offset:27648
	s_waitcnt vmcnt(8)
	ds_write_b128 v208, v[104:107] offset:32256
	s_waitcnt lgkmcnt(0)
	s_barrier
	v_lshl_add_u64 v[210:211], v[164:165], 0, v[132:133]
	v_lshl_add_u64 v[212:213], v[162:163], 0, v[132:133]
	s_nop 0
	v_readfirstlane_b32 s30, v210
	v_readfirstlane_b32 s31, v211
	v_readfirstlane_b32 s34, v212
	v_readfirstlane_b32 s35, v213
	s_nop 1
	v_subrev_u32_e32 v218, s30, v210
	v_subrev_u32_e32 v222, s34, v212
	v_lshl_add_u64 v[214:215], v[166:167], 0, v[132:133]
	v_lshl_add_u64 v[216:217], v[172:173], 0, v[132:133]
	v_subrev_u32_e32 v219, s30, v214
	v_subrev_u32_e32 v223, s34, v216
	v_lshl_add_u64 v[214:215], v[168:169], 0, v[132:133]
	v_lshl_add_u64 v[216:217], v[174:175], 0, v[132:133]
	v_subrev_u32_e32 v220, s30, v214
	v_subrev_u32_e32 v224, s34, v216
	v_lshl_add_u64 v[214:215], v[170:171], 0, v[132:133]
	v_lshl_add_u64 v[216:217], v[176:177], 0, v[132:133]
	v_subrev_u32_e32 v221, s30, v214
	v_subrev_u32_e32 v225, s34, v216
	v_mov_b32_e32 v166, v218
	v_mov_b32_e32 v170, v222
	v_mov_b32_e32 v167, v219
	v_mov_b32_e32 v171, v223
	v_mov_b32_e32 v168, v220
	v_mov_b32_e32 v172, v224
	v_mov_b32_e32 v169, v221
	v_mov_b32_e32 v173, v225
	ds_read_b128 v[210:213], v130
	ds_read_b128 v[214:217], v130 offset:4608
	ds_read_b128 v[218:221], v131 offset:18432
	ds_read_b128 v[222:225], v131 offset:23040
; template <class LA>
; DI void gemm_tile(const LA& la, int m0, const u16* __restrict__ Bm, long ldb, int K, f32x16 (&acc)[2][2], char* lds, int tid) {
;     ...
;   const int arow = (wm * 64 + (lane & 31)) * 144 + (lane >> 5) * 16;
;   const int brow = 18432 + (wn * 64 + (lane & 31)) * 144 + (lane >> 5) * 16;
;   char* lds0 = lds;
;   char* lds1 = lds + 36864;
;   __syncthreads();
;   GT_LOAD(p, 0)
;   if (nk > 1) { GT_LOAD(q, 64) }
;   GT_STORE(p, lds0)
;   __syncthreads();
; #pragma unroll 1
;   for (int kt = 0; kt < nk; kt += 2) {
;     if (kt + 2 < nk) { GT_LOAD(p, (kt + 2) * 64) }
;     GT_COMPUTE(lds0)
;     if (kt + 1 < nk) { GT_STORE(q, lds1) }
;     __syncthreads();
;     if (kt + 1 >= nk) break;
;     if (kt + 3 < nk) { GT_LOAD(q, (kt + 3) * 64) }
;     GT_COMPUTE(lds1)
;     if (kt + 2 < nk) { GT_STORE(p, lds0) }
;     __syncthreads();
;   }
.Lp5n_loop:
	ds_read_b128 v[226:229], v130 offset:32
	ds_read_b128 v[230:233], v130 offset:4640
	ds_read_b128 v[234:237], v131 offset:18464
	ds_read_b128 v[238:241], v131 offset:23072
	s_waitcnt lgkmcnt(4)
	v_mfma_f32_32x32x16_bf16 v[48:63], v[210:213], v[218:221], v[48:63]
	global_load_dwordx4 v[64:67], v166, s[30:31] offset:256
	v_mfma_f32_32x32x16_bf16 v[32:47], v[210:213], v[222:225], v[32:47]
	global_load_dwordx4 v[68:71], v167, s[30:31] offset:256
	v_mfma_f32_32x32x16_bf16 v[16:31], v[214:217], v[218:221], v[16:31]
	global_load_dwordx4 v[72:75], v168, s[30:31] offset:256
	ds_read_b128 v[242:245], v130 offset:64
	ds_read_b128 v[246:249], v130 offset:4672
	s_waitcnt vmcnt(3)
	v_mfma_f32_32x32x16_bf16 v[0:15], v[214:217], v[222:225], v[0:15]
	global_load_dwordx4 v[80:83], v169, s[30:31] offset:256
	ds_read_b128 v[250:253], v131 offset:18496
	ds_read_b128 v[162:165], v131 offset:23104
	ds_write_b128 v208, v[76:79] offset:36864
	s_waitcnt lgkmcnt(5)
	v_mfma_f32_32x32x16_bf16 v[48:63], v[226:229], v[234:237], v[48:63]
	global_load_dwordx4 v[88:91], v170, s[34:35] offset:256
	ds_write_b128 v208, v[84:87] offset:41472
	v_mfma_f32_32x32x16_bf16 v[32:47], v[226:229], v[238:241], v[32:47]
	global_load_dwordx4 v[92:95], v171, s[34:35] offset:256
	ds_write_b128 v208, v[100:103] offset:46080
	v_mfma_f32_32x32x16_bf16 v[16:31], v[230:233], v[234:237], v[16:31]
	global_load_dwordx4 v[96:99], v172, s[34:35] offset:256
	ds_write_b128 v208, v[108:111] offset:50688
	ds_read_b128 v[210:213], v130 offset:96
	ds_read_b128 v[214:217], v130 offset:4704
	v_mfma_f32_32x32x16_bf16 v[0:15], v[230:233], v[238:241], v[0:15]
	global_load_dwordx4 v[104:107], v173, s[34:35] offset:256
	ds_write_b128 v208, v[112:115] offset:55296
	ds_read_b128 v[218:221], v131 offset:18528
	ds_read_b128 v[222:225], v131 offset:23136
	s_waitcnt lgkmcnt(9)
	v_mfma_f32_32x32x16_bf16 v[48:63], v[242:245], v[250:253], v[48:63]
	ds_write_b128 v208, v[116:119] offset:59904
	v_mfma_f32_32x32x16_bf16 v[32:47], v[242:245], v[162:165], v[32:47]
	ds_write_b128 v208, v[120:123] offset:64512
	v_mfma_f32_32x32x16_bf16 v[16:31], v[246:249], v[250:253], v[16:31]
	ds_write_b128 v129, v[124:127] offset:13824
	v_mfma_f32_32x32x16_bf16 v[0:15], v[246:249], v[162:165], v[0:15]
	s_waitcnt lgkmcnt(0)
	s_barrier
	v_mfma_f32_32x32x16_bf16 v[48:63], v[210:213], v[218:221], v[48:63]
	ds_read_b128 v[226:229], v130 offset:36864
	ds_read_b128 v[230:233], v130 offset:41472
	v_mfma_f32_32x32x16_bf16 v[32:47], v[210:213], v[222:225], v[32:47]
	ds_read_b128 v[234:237], v131 offset:55296
	ds_read_b128 v[238:241], v131 offset:59904
	v_mfma_f32_32x32x16_bf16 v[16:31], v[214:217], v[218:221], v[16:31]
	v_mfma_f32_32x32x16_bf16 v[0:15], v[214:217], v[222:225], v[0:15]
	ds_read_b128 v[242:245], v130 offset:36896
	ds_read_b128 v[246:249], v130 offset:41504
	ds_read_b128 v[250:253], v131 offset:55328
	ds_read_b128 v[162:165], v131 offset:59936
	s_waitcnt lgkmcnt(4)
	v_mfma_f32_32x32x16_bf16 v[48:63], v[226:229], v[234:237], v[48:63]
	global_load_dwordx4 v[76:79], v166, s[30:31] offset:384
	v_mfma_f32_32x32x16_bf16 v[32:47], v[226:229], v[238:241], v[32:47]
	global_load_dwordx4 v[84:87], v167, s[30:31] offset:384
	v_mfma_f32_32x32x16_bf16 v[16:31], v[230:233], v[234:237], v[16:31]
	global_load_dwordx4 v[100:103], v168, s[30:31] offset:384
	ds_read_b128 v[210:213], v130 offset:36928
	ds_read_b128 v[214:217], v130 offset:41536
	s_waitcnt vmcnt(3)
	v_mfma_f32_32x32x16_bf16 v[0:15], v[230:233], v[238:241], v[0:15]
	global_load_dwordx4 v[108:111], v169, s[30:31] offset:384
	ds_read_b128 v[218:221], v131 offset:55360
	ds_read_b128 v[222:225], v131 offset:59968
	ds_write_b128 v208, v[64:67]
	s_waitcnt lgkmcnt(5)
	v_mfma_f32_32x32x16_bf16 v[48:63], v[242:245], v[250:253], v[48:63]
	global_load_dwordx4 v[112:115], v170, s[34:35] offset:384
	ds_write_b128 v208, v[68:71] offset:4608
	v_mfma_f32_32x32x16_bf16 v[32:47], v[242:245], v[162:165], v[32:47]
	global_load_dwordx4 v[116:119], v171, s[34:35] offset:384
	ds_write_b128 v208, v[72:75] offset:9216
	v_mfma_f32_32x32x16_bf16 v[16:31], v[246:249], v[250:253], v[16:31]
	global_load_dwordx4 v[120:123], v172, s[34:35] offset:384
	ds_write_b128 v208, v[80:83] offset:13824
	ds_read_b128 v[226:229], v130 offset:36960
	ds_read_b128 v[230:233], v130 offset:41568
	v_mfma_f32_32x32x16_bf16 v[0:15], v[246:249], v[162:165], v[0:15]
	global_load_dwordx4 v[124:127], v173, s[34:35] offset:384
	ds_write_b128 v208, v[88:91] offset:18432
	ds_read_b128 v[234:237], v131 offset:55392
	ds_read_b128 v[238:241], v131 offset:60000
	s_waitcnt lgkmcnt(9)
	v_mfma_f32_32x32x16_bf16 v[48:63], v[210:213], v[218:221], v[48:63]
	ds_write_b128 v208, v[92:95] offset:23040
	v_mfma_f32_32x32x16_bf16 v[32:47], v[210:213], v[222:225], v[32:47]
	ds_write_b128 v208, v[96:99] offset:27648
	v_mfma_f32_32x32x16_bf16 v[16:31], v[214:217], v[218:221], v[16:31]
	ds_write_b128 v208, v[104:107] offset:32256
	v_mfma_f32_32x32x16_bf16 v[0:15], v[214:217], v[222:225], v[0:15]
	s_waitcnt lgkmcnt(0)
	s_barrier
	v_mfma_f32_32x32x16_bf16 v[48:63], v[226:229], v[234:237], v[48:63]
	ds_read_b128 v[242:245], v130
	ds_read_b128 v[246:249], v130 offset:4608
	v_mfma_f32_32x32x16_bf16 v[32:47], v[226:229], v[238:241], v[32:47]
	ds_read_b128 v[250:253], v131 offset:18432
	ds_read_b128 v[162:165], v131 offset:23040
	v_mfma_f32_32x32x16_bf16 v[16:31], v[230:233], v[234:237], v[16:31]
	v_mfma_f32_32x32x16_bf16 v[0:15], v[230:233], v[238:241], v[0:15]
	s_add_i32 s15, s15, 2
	s_cmp_ge_u32 s15, s5
	s_cbranch_scc1 .Lp5n_exit
; template <class LA>
; DI void gemm_tile(const LA& la, int m0, const u16* __restrict__ Bm, long ldb, int K, f32x16 (&acc)[2][2], char* lds, int tid) {
;     ...
;   const int arow = (wm * 64 + (lane & 31)) * 144 + (lane >> 5) * 16;
;   const int brow = 18432 + (wn * 64 + (lane & 31)) * 144 + (lane >> 5) * 16;
;   char* lds0 = lds;
;   char* lds1 = lds + 36864;
;   __syncthreads();
;   GT_LOAD(p, 0)
;   if (nk > 1) { GT_LOAD(q, 64) }
;   GT_STORE(p, lds0)
;   __syncthreads();
; #pragma unroll 1
;   for (int kt = 0; kt < nk; kt += 2) {
;     if (kt + 2 < nk) { GT_LOAD(p, (kt + 2) * 64) }
;     GT_COMPUTE(lds0)
;     if (kt + 1 < nk) { GT_STORE(q, lds1) }
;     __syncthreads();
;     if (kt + 1 >= nk) break;
;     if (kt + 3 < nk) { GT_LOAD(q, (kt + 3) * 64) }
;     GT_COMPUTE(lds1)
;     if (kt + 2 < nk) { GT_STORE(p, lds0) }
;     __syncthreads();
;   }
	ds_read_b128 v[210:213], v130 offset:32
	ds_read_b128 v[214:217], v130 offset:4640
	ds_read_b128 v[218:221], v131 offset:18464
	ds_read_b128 v[222:225], v131 offset:23072
	s_waitcnt lgkmcnt(4)
	v_mfma_f32_32x32x16_bf16 v[48:63], v[242:245], v[250:253], v[48:63]
	global_load_dwordx4 v[64:67], v166, s[30:31] offset:512
	v_mfma_f32_32x32x16_bf16 v[32:47], v[242:245], v[162:165], v[32:47]
	global_load_dwordx4 v[68:71], v167, s[30:31] offset:512
	v_mfma_f32_32x32x16_bf16 v[16:31], v[246:249], v[250:253], v[16:31]
	global_load_dwordx4 v[72:75], v168, s[30:31] offset:512
	ds_read_b128 v[226:229], v130 offset:64
	ds_read_b128 v[230:233], v130 offset:4672
	s_waitcnt vmcnt(3)
	v_mfma_f32_32x32x16_bf16 v[0:15], v[246:249], v[162:165], v[0:15]
	global_load_dwordx4 v[80:83], v169, s[30:31] offset:512
	ds_read_b128 v[234:237], v131 offset:18496
	ds_read_b128 v[238:241], v131 offset:23104
	ds_write_b128 v208, v[76:79] offset:36864
	s_waitcnt lgkmcnt(5)
	v_mfma_f32_32x32x16_bf16 v[48:63], v[210:213], v[218:221], v[48:63]
	global_load_dwordx4 v[88:91], v170, s[34:35] offset:512
	ds_write_b128 v208, v[84:87] offset:41472
	v_mfma_f32_32x32x16_bf16 v[32:47], v[210:213], v[222:225], v[32:47]
	global_load_dwordx4 v[92:95], v171, s[34:35] offset:512
	ds_write_b128 v208, v[100:103] offset:46080
	v_mfma_f32_32x32x16_bf16 v[16:31], v[214:217], v[218:221], v[16:31]
	global_load_dwordx4 v[96:99], v172, s[34:35] offset:512
	ds_write_b128 v208, v[108:111] offset:50688
	ds_read_b128 v[242:245], v130 offset:96
	ds_read_b128 v[246:249], v130 offset:4704
	v_mfma_f32_32x32x16_bf16 v[0:15], v[214:217], v[222:225], v[0:15]
	global_load_dwordx4 v[104:107], v173, s[34:35] offset:512
	ds_write_b128 v208, v[112:115] offset:55296
	ds_read_b128 v[250:253], v131 offset:18528
	ds_read_b128 v[162:165], v131 offset:23136
	s_waitcnt lgkmcnt(9)
	v_mfma_f32_32x32x16_bf16 v[48:63], v[226:229], v[234:237], v[48:63]
	ds_write_b128 v208, v[116:119] offset:59904
	v_mfma_f32_32x32x16_bf16 v[32:47], v[226:229], v[238:241], v[32:47]
	ds_write_b128 v208, v[120:123] offset:64512
	v_mfma_f32_32x32x16_bf16 v[16:31], v[230:233], v[234:237], v[16:31]
	ds_write_b128 v129, v[124:127] offset:13824
	v_mfma_f32_32x32x16_bf16 v[0:15], v[230:233], v[238:241], v[0:15]
	s_waitcnt lgkmcnt(0)
	s_barrier
	v_mfma_f32_32x32x16_bf16 v[48:63], v[242:245], v[250:253], v[48:63]
	ds_read_b128 v[210:213], v130 offset:36864
	ds_read_b128 v[214:217], v130 offset:41472
	v_mfma_f32_32x32x16_bf16 v[32:47], v[242:245], v[162:165], v[32:47]
	ds_read_b128 v[218:221], v131 offset:55296
	ds_read_b128 v[222:225], v131 offset:59904
	v_mfma_f32_32x32x16_bf16 v[16:31], v[246:249], v[250:253], v[16:31]
	v_mfma_f32_32x32x16_bf16 v[0:15], v[246:249], v[162:165], v[0:15]
	ds_read_b128 v[226:229], v130 offset:36896
	ds_read_b128 v[230:233], v130 offset:41504
	ds_read_b128 v[234:237], v131 offset:55328
	ds_read_b128 v[238:241], v131 offset:59936
	s_waitcnt lgkmcnt(4)
	v_mfma_f32_32x32x16_bf16 v[48:63], v[210:213], v[218:221], v[48:63]
	global_load_dwordx4 v[76:79], v166, s[30:31] offset:640
	v_mfma_f32_32x32x16_bf16 v[32:47], v[210:213], v[222:225], v[32:47]
	global_load_dwordx4 v[84:87], v167, s[30:31] offset:640
	v_mfma_f32_32x32x16_bf16 v[16:31], v[214:217], v[218:221], v[16:31]
	global_load_dwordx4 v[100:103], v168, s[30:31] offset:640
	ds_read_b128 v[242:245], v130 offset:36928
	ds_read_b128 v[246:249], v130 offset:41536
	s_waitcnt vmcnt(3)
	v_mfma_f32_32x32x16_bf16 v[0:15], v[214:217], v[222:225], v[0:15]
	global_load_dwordx4 v[108:111], v169, s[30:31] offset:640
	ds_read_b128 v[250:253], v131 offset:55360
	ds_read_b128 v[162:165], v131 offset:59968
	ds_write_b128 v208, v[64:67]
	s_waitcnt lgkmcnt(5)
	v_mfma_f32_32x32x16_bf16 v[48:63], v[226:229], v[234:237], v[48:63]
	global_load_dwordx4 v[112:115], v170, s[34:35] offset:640
	ds_write_b128 v208, v[68:71] offset:4608
	v_mfma_f32_32x32x16_bf16 v[32:47], v[226:229], v[238:241], v[32:47]
	global_load_dwordx4 v[116:119], v171, s[34:35] offset:640
	ds_write_b128 v208, v[72:75] offset:9216
	v_mfma_f32_32x32x16_bf16 v[16:31], v[230:233], v[234:237], v[16:31]
	global_load_dwordx4 v[120:123], v172, s[34:35] offset:640
	ds_write_b128 v208, v[80:83] offset:13824
	ds_read_b128 v[210:213], v130 offset:36960
	ds_read_b128 v[214:217], v130 offset:41568
	v_mfma_f32_32x32x16_bf16 v[0:15], v[230:233], v[238:241], v[0:15]
	global_load_dwordx4 v[124:127], v173, s[34:35] offset:640
	ds_write_b128 v208, v[88:91] offset:18432
	ds_read_b128 v[218:221], v131 offset:55392
	ds_read_b128 v[222:225], v131 offset:60000
	s_waitcnt lgkmcnt(9)
	v_mfma_f32_32x32x16_bf16 v[48:63], v[242:245], v[250:253], v[48:63]
	ds_write_b128 v208, v[92:95] offset:23040
	v_mfma_f32_32x32x16_bf16 v[32:47], v[242:245], v[162:165], v[32:47]
	ds_write_b128 v208, v[96:99] offset:27648
	v_mfma_f32_32x32x16_bf16 v[16:31], v[246:249], v[250:253], v[16:31]
	ds_write_b128 v208, v[104:107] offset:32256
	v_mfma_f32_32x32x16_bf16 v[0:15], v[246:249], v[162:165], v[0:15]
	s_waitcnt lgkmcnt(0)
	s_barrier
	v_mfma_f32_32x32x16_bf16 v[48:63], v[210:213], v[218:221], v[48:63]
	ds_read_b128 v[226:229], v130
	ds_read_b128 v[230:233], v130 offset:4608
	v_mfma_f32_32x32x16_bf16 v[32:47], v[210:213], v[222:225], v[32:47]
	ds_read_b128 v[234:237], v131 offset:18432
	ds_read_b128 v[238:241], v131 offset:23040
	v_mfma_f32_32x32x16_bf16 v[16:31], v[214:217], v[218:221], v[16:31]
	v_mfma_f32_32x32x16_bf16 v[0:15], v[214:217], v[222:225], v[0:15]
	s_add_i32 s15, s15, 2
	s_cmp_ge_u32 s15, s5
	s_cbranch_scc1 .Lp5n_exit
; template <class LA>
; DI void gemm_tile(const LA& la, int m0, const u16* __restrict__ Bm, long ldb, int K, f32x16 (&acc)[2][2], char* lds, int tid) {
;     ...
;   const int arow = (wm * 64 + (lane & 31)) * 144 + (lane >> 5) * 16;
;   const int brow = 18432 + (wn * 64 + (lane & 31)) * 144 + (lane >> 5) * 16;
;   char* lds0 = lds;
;   char* lds1 = lds + 36864;
;   __syncthreads();
;   GT_LOAD(p, 0)
;   if (nk > 1) { GT_LOAD(q, 64) }
;   GT_STORE(p, lds0)
;   __syncthreads();
; #pragma unroll 1
;   for (int kt = 0; kt < nk; kt += 2) {
;     if (kt + 2 < nk) { GT_LOAD(p, (kt + 2) * 64) }
;     GT_COMPUTE(lds0)
;     if (kt + 1 < nk) { GT_STORE(q, lds1) }
;     __syncthreads();
;     if (kt + 1 >= nk) break;
;     if (kt + 3 < nk) { GT_LOAD(q, (kt + 3) * 64) }
;     GT_COMPUTE(lds1)
;     if (kt + 2 < nk) { GT_STORE(p, lds0) }
;     __syncthreads();
;   }
	ds_read_b128 v[242:245], v130 offset:32
	ds_read_b128 v[246:249], v130 offset:4640
	ds_read_b128 v[250:253], v131 offset:18464
	ds_read_b128 v[162:165], v131 offset:23072
	s_waitcnt lgkmcnt(4)
	v_mfma_f32_32x32x16_bf16 v[48:63], v[226:229], v[234:237], v[48:63]
	global_load_dwordx4 v[64:67], v166, s[30:31] offset:768
	v_mfma_f32_32x32x16_bf16 v[32:47], v[226:229], v[238:241], v[32:47]
	global_load_dwordx4 v[68:71], v167, s[30:31] offset:768
	v_mfma_f32_32x32x16_bf16 v[16:31], v[230:233], v[234:237], v[16:31]
	global_load_dwordx4 v[72:75], v168, s[30:31] offset:768
	ds_read_b128 v[210:213], v130 offset:64
	ds_read_b128 v[214:217], v130 offset:4672
	s_waitcnt vmcnt(3)
	v_mfma_f32_32x32x16_bf16 v[0:15], v[230:233], v[238:241], v[0:15]
	global_load_dwordx4 v[80:83], v169, s[30:31] offset:768
	ds_read_b128 v[218:221], v131 offset:18496
	ds_read_b128 v[222:225], v131 offset:23104
	ds_write_b128 v208, v[76:79] offset:36864
	s_waitcnt lgkmcnt(5)
	v_mfma_f32_32x32x16_bf16 v[48:63], v[242:245], v[250:253], v[48:63]
	global_load_dwordx4 v[88:91], v170, s[34:35] offset:768
	ds_write_b128 v208, v[84:87] offset:41472
	v_mfma_f32_32x32x16_bf16 v[32:47], v[242:245], v[162:165], v[32:47]
	global_load_dwordx4 v[92:95], v171, s[34:35] offset:768
	ds_write_b128 v208, v[100:103] offset:46080
	v_mfma_f32_32x32x16_bf16 v[16:31], v[246:249], v[250:253], v[16:31]
	global_load_dwordx4 v[96:99], v172, s[34:35] offset:768
	ds_write_b128 v208, v[108:111] offset:50688
	ds_read_b128 v[226:229], v130 offset:96
	ds_read_b128 v[230:233], v130 offset:4704
	v_mfma_f32_32x32x16_bf16 v[0:15], v[246:249], v[162:165], v[0:15]
	global_load_dwordx4 v[104:107], v173, s[34:35] offset:768
	ds_write_b128 v208, v[112:115] offset:55296
	ds_read_b128 v[234:237], v131 offset:18528
	ds_read_b128 v[238:241], v131 offset:23136
	s_waitcnt lgkmcnt(9)
	v_mfma_f32_32x32x16_bf16 v[48:63], v[210:213], v[218:221], v[48:63]
	ds_write_b128 v208, v[116:119] offset:59904
	v_mfma_f32_32x32x16_bf16 v[32:47], v[210:213], v[222:225], v[32:47]
	ds_write_b128 v208, v[120:123] offset:64512
	v_mfma_f32_32x32x16_bf16 v[16:31], v[214:217], v[218:221], v[16:31]
	ds_write_b128 v129, v[124:127] offset:13824
	v_mfma_f32_32x32x16_bf16 v[0:15], v[214:217], v[222:225], v[0:15]
	s_waitcnt lgkmcnt(0)
	s_barrier
	v_mfma_f32_32x32x16_bf16 v[48:63], v[226:229], v[234:237], v[48:63]
	ds_read_b128 v[242:245], v130 offset:36864
	ds_read_b128 v[246:249], v130 offset:41472
	v_mfma_f32_32x32x16_bf16 v[32:47], v[226:229], v[238:241], v[32:47]
	ds_read_b128 v[250:253], v131 offset:55296
	ds_read_b128 v[162:165], v131 offset:59904
	v_mfma_f32_32x32x16_bf16 v[16:31], v[230:233], v[234:237], v[16:31]
	v_mfma_f32_32x32x16_bf16 v[0:15], v[230:233], v[238:241], v[0:15]
	ds_read_b128 v[210:213], v130 offset:36896
	ds_read_b128 v[214:217], v130 offset:41504
	ds_read_b128 v[218:221], v131 offset:55328
	ds_read_b128 v[222:225], v131 offset:59936
	s_waitcnt lgkmcnt(4)
	v_mfma_f32_32x32x16_bf16 v[48:63], v[242:245], v[250:253], v[48:63]
	global_load_dwordx4 v[76:79], v166, s[30:31] offset:896
	v_mfma_f32_32x32x16_bf16 v[32:47], v[242:245], v[162:165], v[32:47]
	global_load_dwordx4 v[84:87], v167, s[30:31] offset:896
	v_mfma_f32_32x32x16_bf16 v[16:31], v[246:249], v[250:253], v[16:31]
	global_load_dwordx4 v[100:103], v168, s[30:31] offset:896
	ds_read_b128 v[226:229], v130 offset:36928
	ds_read_b128 v[230:233], v130 offset:41536
	s_waitcnt vmcnt(3)
	v_mfma_f32_32x32x16_bf16 v[0:15], v[246:249], v[162:165], v[0:15]
	global_load_dwordx4 v[108:111], v169, s[30:31] offset:896
	ds_read_b128 v[234:237], v131 offset:55360
	ds_read_b128 v[238:241], v131 offset:59968
	ds_write_b128 v208, v[64:67]
	s_waitcnt lgkmcnt(5)
	v_mfma_f32_32x32x16_bf16 v[48:63], v[210:213], v[218:221], v[48:63]
	global_load_dwordx4 v[112:115], v170, s[34:35] offset:896
	ds_write_b128 v208, v[68:71] offset:4608
	v_mfma_f32_32x32x16_bf16 v[32:47], v[210:213], v[222:225], v[32:47]
	global_load_dwordx4 v[116:119], v171, s[34:35] offset:896
	ds_write_b128 v208, v[72:75] offset:9216
	v_mfma_f32_32x32x16_bf16 v[16:31], v[214:217], v[218:221], v[16:31]
	global_load_dwordx4 v[120:123], v172, s[34:35] offset:896
	ds_write_b128 v208, v[80:83] offset:13824
	ds_read_b128 v[242:245], v130 offset:36960
	ds_read_b128 v[246:249], v130 offset:41568
	v_mfma_f32_32x32x16_bf16 v[0:15], v[214:217], v[222:225], v[0:15]
	global_load_dwordx4 v[124:127], v173, s[34:35] offset:896
	ds_write_b128 v208, v[88:91] offset:18432
	ds_read_b128 v[250:253], v131 offset:55392
	ds_read_b128 v[162:165], v131 offset:60000
	s_waitcnt lgkmcnt(9)
	v_mfma_f32_32x32x16_bf16 v[48:63], v[226:229], v[234:237], v[48:63]
	ds_write_b128 v208, v[92:95] offset:23040
	v_mfma_f32_32x32x16_bf16 v[32:47], v[226:229], v[238:241], v[32:47]
	ds_write_b128 v208, v[96:99] offset:27648
	v_mfma_f32_32x32x16_bf16 v[16:31], v[230:233], v[234:237], v[16:31]
	ds_write_b128 v208, v[104:107] offset:32256
	v_mfma_f32_32x32x16_bf16 v[0:15], v[230:233], v[238:241], v[0:15]
	s_waitcnt lgkmcnt(0)
	s_barrier
	v_mfma_f32_32x32x16_bf16 v[48:63], v[242:245], v[250:253], v[48:63]
	ds_read_b128 v[210:213], v130
	ds_read_b128 v[214:217], v130 offset:4608
	v_mfma_f32_32x32x16_bf16 v[32:47], v[242:245], v[162:165], v[32:47]
	ds_read_b128 v[218:221], v131 offset:18432
	ds_read_b128 v[222:225], v131 offset:23040
	v_mfma_f32_32x32x16_bf16 v[16:31], v[246:249], v[250:253], v[16:31]
	v_mfma_f32_32x32x16_bf16 v[0:15], v[246:249], v[162:165], v[0:15]
	s_add_i32 s15, s15, 2
	s_cmp_ge_u32 s15, s5
	s_cbranch_scc1 .Lp5n_exit
	s_add_u32 s30, s30, 0x300
	s_addc_u32 s31, s31, 0
	s_add_u32 s34, s34, 0x300
	s_addc_u32 s35, s35, 0
	s_branch .Lp5n_loop
.Lp5n_exit:
	s_branch .LBB0_405
.LBB0_400:
	s_add_i32 s15, s15, 2
	s_cmp_ge_u32 s16, s5
	v_lshl_add_u64 v[162:163], v[162:163], 0, s[66:67]
	v_lshl_add_u64 v[172:173], v[172:173], 0, s[66:67]
	v_lshl_add_u64 v[174:175], v[174:175], 0, s[66:67]
	v_lshl_add_u64 v[176:177], v[176:177], 0, s[66:67]
	v_lshl_add_u64 v[164:165], v[164:165], 0, s[66:67]
	v_lshl_add_u64 v[166:167], v[166:167], 0, s[66:67]
	v_lshl_add_u64 v[168:169], v[168:169], 0, s[66:67]
	v_lshl_add_u64 v[170:171], v[170:171], 0, s[66:67]
	s_cselect_b64 s[8:9], -1, 0
	s_waitcnt lgkmcnt(0)
	s_barrier
	s_and_b64 vcc, exec, s[8:9]
	s_cbranch_vccz .LBB0_405
	s_branch .LBB0_398

; DI float bflo(unsigned v) { return __uint_as_float(v << 16); }
; DI float bfhi(unsigned v) { return __uint_as_float(v & 0xffff0000u); }
; template <int MASK>
; __global__ void __launch_bounds__(256, 2) fwd_megakernel_t(Params p) {
;     ...
;       for (int row = blockIdx.x * 4 + wave; row < T_ * 2; row += gridDim.x * 4) {
;         const int t = row >> 1, h2 = row & 1;
;         const float l0 = lse[t * 6 + h2], l1 = lse[t * 6 + 2 + h2], l2 = lse[t * 6 + 4 + h2];
;         const float mx = fmaxf(l0, fmaxf(l1, l2));
;         float e0 = __expf(l0 - mx), e1 = __expf(l1 - mx), e2 = __expf(l2 - mx);
;         const float inv = 1.f / (e0 + e1 + e2);
;         e0 *= inv; e1 *= inv; e2 *= inv;
;         const unsigned* src = (const unsigned*)(og + (size_t)t * 768 + h2 * 128) + lane;
;         const unsigned a = src[0], b = src[128], c = src[256];
;         ((unsigned*)(odil + (size_t)t * 256 + h2 * 128))[lane] =
;             pack2(e0 * bflo(a) + e1 * bflo(b) + e2 * bflo(c), e0 * bfhi(a) + e1 * bfhi(b) + e2 * bfhi(c));
;       }
.LBB0_422:
	v_ashrrev_i32_e32 v4, 1, v6
	v_mul_lo_u32 v5, v4, 6
	v_or_b32_e32 v8, v5, v7
	v_ashrrev_i32_e32 v9, 31, v8
	v_lshl_add_u64 v[10:11], v[8:9], 2, s[30:31]
	global_load_dword v5, v[10:11], off
	v_add_u32_e32 v10, 2, v8
	v_add_u32_e32 v8, 4, v8
	v_ashrrev_i32_e32 v11, 31, v10
	v_ashrrev_i32_e32 v9, 31, v8
	v_lshl_add_u64 v[10:11], v[10:11], 2, s[30:31]
	v_lshl_add_u64 v[8:9], v[8:9], 2, s[30:31]
	global_load_dword v10, v[10:11], off
	v_add_u32_e32 v6, s75, v6
	global_load_dword v11, v[8:9], off
	v_mad_i64_i32 v[18:19], s[8:9], v4, s47, v[0:1]
	global_load_dword v20, v[18:19], off
	global_load_dword v21, v[18:19], off offset:512
	global_load_dword v22, v[18:19], off offset:1024
	s_waitcnt vmcnt(3)
	v_max3_f32 v12, v5, v10, v11
	v_sub_f32_e32 v5, v5, v12
	v_mul_f32_e32 v5, 0x3fb8aa3b, v5
	v_exp_f32_e32 v9, v5
	v_sub_f32_e32 v5, v10, v12
	v_mul_f32_e32 v5, 0x3fb8aa3b, v5
	v_exp_f32_e32 v8, v5
	v_sub_f32_e32 v5, v11, v12
	v_mul_f32_e32 v5, 0x3fb8aa3b, v5
	v_exp_f32_e32 v5, v5
	v_add_f32_e32 v10, v9, v8
	v_add_f32_e32 v10, v5, v10
	v_div_scale_f32 v11, s[8:9], v10, v10, 1.0
	v_rcp_f32_e32 v12, v11
	s_nop 0
	v_fma_f32 v13, -v11, v12, 1.0
	v_fmac_f32_e32 v12, v13, v12
	v_div_scale_f32 v13, vcc, 1.0, v10, 1.0
	v_mul_f32_e32 v14, v13, v12
	v_fma_f32 v15, -v11, v14, v13
	v_fmac_f32_e32 v14, v15, v12
	v_fma_f32 v11, -v11, v14, v13
	v_div_fmas_f32 v11, v11, v12, v14
	v_div_fixup_f32 v10, v11, v10, 1.0
	v_mul_f32_e32 v12, v5, v10
	v_ashrrev_i32_e32 v5, 31, v4
	s_movk_i32 s8, 0x7fff
	v_lshlrev_b64 v[4:5], 9, v[4:5]
	v_cmp_lt_i32_e32 vcc, s8, v6
	v_lshl_add_u64 v[4:5], v[2:3], 0, v[4:5]
	s_or_b64 s[6:7], vcc, s[6:7]
	s_waitcnt vmcnt(2)
	v_lshlrev_b32_e32 v16, 16, v20
	s_waitcnt vmcnt(0)
	v_pk_mul_f32 v[8:9], v[8:9], v[10:11] op_sel_hi:[1,0]
	v_lshlrev_b32_e32 v10, 16, v21
	v_and_b32_e32 v17, 0xffff0000, v21
	v_lshlrev_b32_e32 v14, 16, v22
	v_and_b32_e32 v15, 0xffff0000, v22
	v_and_b32_e32 v11, 0xffff0000, v20
	v_pk_mul_f32 v[16:17], v[8:9], v[16:17] op_sel:[1,0] op_sel_hi:[0,1]
	v_pk_fma_f32 v[8:9], v[8:9], v[10:11], v[16:17]
	s_nop 0
	v_pk_fma_f32 v[8:9], v[12:13], v[14:15], v[8:9] op_sel_hi:[0,1,1]
	v_cvt_pk_bf16_f32 v8, v8, v9
	global_store_dword v[4:5], v8, off
	s_andn2_b64 exec, exec, s[6:7]
	s_cbranch_execnz .LBB0_422

; #define MFMA32(a, b, c) __builtin_amdgcn_mfma_f32_32x32x16_bf16((a), (b), (c), 0, 0, 0)
; template <int MODE>
; DI void attn_item(const u16* __restrict__ Qp, const u16* __restrict__ Kp, const u16* __restrict__ VTp, int q0,
;                   int kt_lo, int kt_hi, u16* __restrict__ Op, int os, float* __restrict__ lsep, int ls, char* lds, int tid) {
;     ...
;     for (int ks = 0; ks < NKS; ks++)
; #pragma unroll
;       for (int mt = 0; mt < NMT; mt++) {
;         const bf16x8 kf = *(const bf16x8*)(Ks + (mt * 32 + c) * KROW + (ks * 16 + h * 8) * 2);
;         st[mt] = MFMA32(kf, qf[ks], st[mt]);
;       }
;     ...
;     } else if (MODE != 1) {
;       float mx = -1e30f;
; #pragma unroll
;       for (int mt = 0; mt < NMT; mt++)
; #pragma unroll
;         for (int r = 0; r < 16; r++) {
;           const int key = kb + mt * 32 + 8 * (r >> 2) + (r & 3);
;           const bool valid = (MODE == 0) ? (key <= myq) : (key <= myq && myq - key <= 128);
;           const float s = valid ? st[mt][r] : -1e30f;
;           st[mt][r] = s;
;           mx = fmaxf(mx, s);
;         }
;       mx = fmaxf(mx, __shfl_xor(mx, 32));
;       const float m_new = fmaxf(m_run, mx);
;       const float alpha = __builtin_amdgcn_exp2f(m_run - m_new);
.LBB0_439:
	s_bitcmp1_b32 s49, 0
	s_cselect_b32 s39, 0x4a00, 0
	v_add3_u32 v142, s39, v206, v207
	ds_read_b128 v[64:67], v142
	ds_read_b128 v[138:141], v142 offset:32
	s_add_i32 s49, s49, 1
	s_setprio 1
	s_waitcnt lgkmcnt(1)
	v_mfma_f32_32x32x16_bf16 v[64:79], v[64:67], v[80:83], 0
	s_waitcnt lgkmcnt(0)
	v_mfma_f32_32x32x16_bf16 v[64:79], v[138:141], v[84:87], v[64:79]
	ds_read_b128 v[138:141], v142 offset:64
	s_waitcnt lgkmcnt(0)
	v_mfma_f32_32x32x16_bf16 v[64:79], v[138:141], v[88:91], v[64:79]
	ds_read_b128 v[138:141], v142 offset:96
	s_waitcnt lgkmcnt(0)
	v_mfma_f32_32x32x16_bf16 v[64:79], v[138:141], v[92:95], v[64:79]
	ds_read_b128 v[138:141], v142 offset:128
	s_waitcnt lgkmcnt(0)
	v_mfma_f32_32x32x16_bf16 v[64:79], v[138:141], v[96:99], v[64:79]
	ds_read_b128 v[138:141], v142 offset:160
	s_waitcnt lgkmcnt(0)
	v_mfma_f32_32x32x16_bf16 v[64:79], v[138:141], v[100:103], v[64:79]
	ds_read_b128 v[138:141], v142 offset:192
	s_waitcnt lgkmcnt(0)
	v_mfma_f32_32x32x16_bf16 v[64:79], v[138:141], v[104:107], v[64:79]
	ds_read_b128 v[138:141], v142 offset:224
	s_waitcnt lgkmcnt(0)
	v_mfma_f32_32x32x16_bf16 v[64:79], v[138:141], v[108:111], v[64:79]
	s_setprio 0
	v_add_u32_e32 v139, s38, v162
	v_add_u32_e32 v138, 27, v134
	v_cmp_le_i32_e32 vcc, v139, v128
	v_cmp_gt_i32_e64 s[10:11], s65, v138
	s_and_b64 vcc, vcc, s[10:11]
	s_movk_i32 s10, 0xff7e
	s_nop 5
	v_cndmask_b32_e32 v138, v197, v64, vcc
	v_add_u32_e32 v64, s38, v135
	v_cmp_lt_i32_e32 vcc, v139, v128
	v_cmp_lt_i32_e64 s[10:11], s10, v64
	s_and_b64 vcc, vcc, s[10:11]
	v_cndmask_b32_e32 v140, v197, v65, vcc
	v_add_u32_e32 v65, 2, v139
	s_mov_b32 s10, 0xf149f2ca
	v_cmp_le_i32_e32 vcc, v65, v128
	v_add_u32_e32 v65, 25, v134
	v_max3_f32 v64, v138, s10, v140
	v_cmp_gt_i32_e64 s[10:11], s65, v65
	s_and_b64 vcc, vcc, s[10:11]
	v_add_u32_e32 v65, 3, v139
	v_cndmask_b32_e32 v141, v197, v66, vcc
	v_cmp_le_i32_e32 vcc, v65, v128
	v_add_u32_e32 v65, 24, v134
	v_cmp_gt_i32_e64 s[10:11], s65, v65
	s_and_b64 vcc, vcc, s[10:11]
	v_add_u32_e32 v65, 8, v139
	v_cndmask_b32_e32 v142, v197, v67, vcc
	v_cmp_le_i32_e32 vcc, v65, v128
	v_add_u32_e32 v65, 19, v134
	v_cmp_gt_i32_e64 s[10:11], s65, v65
	s_and_b64 vcc, vcc, s[10:11]
	v_add_u32_e32 v65, 9, v139
	v_cndmask_b32_e32 v143, v197, v68, vcc
	v_cmp_le_i32_e32 vcc, v65, v128
	v_add_u32_e32 v65, 18, v134
	v_cmp_gt_i32_e64 s[10:11], s65, v65
	s_and_b64 vcc, vcc, s[10:11]
	v_add_u32_e32 v65, 10, v139
	v_cndmask_b32_e32 v144, v197, v69, vcc
	v_cmp_le_i32_e32 vcc, v65, v128
	v_add_u32_e32 v65, 17, v134
	v_cmp_gt_i32_e64 s[10:11], s65, v65
	s_and_b64 vcc, vcc, s[10:11]
	v_add_u32_e32 v65, 11, v139
	v_cndmask_b32_e32 v145, v197, v70, vcc
	v_cmp_le_i32_e32 vcc, v65, v128
	v_add_u32_e32 v65, 16, v134
	v_cmp_gt_i32_e64 s[10:11], s65, v65
	s_and_b64 vcc, vcc, s[10:11]
	v_add_u32_e32 v65, 16, v139
	v_cndmask_b32_e32 v146, v197, v71, vcc
	v_cmp_le_i32_e32 vcc, v65, v128
	v_add_u32_e32 v65, 11, v134
	v_cmp_gt_i32_e64 s[10:11], s65, v65
	s_and_b64 vcc, vcc, s[10:11]
	v_add_u32_e32 v65, 17, v139
	v_cndmask_b32_e32 v147, v197, v72, vcc
	v_cmp_le_i32_e32 vcc, v65, v128
	v_add_u32_e32 v65, 10, v134
	v_cmp_gt_i32_e64 s[10:11], s65, v65
	s_and_b64 vcc, vcc, s[10:11]
	v_add_u32_e32 v65, 18, v139
	v_cndmask_b32_e32 v150, v197, v73, vcc
	v_cmp_le_i32_e32 vcc, v65, v128
	v_add_u32_e32 v65, 9, v134
	v_cmp_gt_i32_e64 s[10:11], s65, v65
	s_and_b64 vcc, vcc, s[10:11]
	v_add_u32_e32 v65, 19, v139
	v_cndmask_b32_e32 v168, v197, v74, vcc
	v_cmp_le_i32_e32 vcc, v65, v128
	v_add_u32_e32 v65, 8, v134
	v_cmp_gt_i32_e64 s[10:11], s65, v65
	s_and_b64 vcc, vcc, s[10:11]
	v_add_u32_e32 v65, 24, v139
	v_cndmask_b32_e32 v170, v197, v75, vcc
	v_cmp_le_i32_e32 vcc, v65, v128
	v_add_u32_e32 v65, 3, v134
	v_cmp_gt_i32_e64 s[10:11], s65, v65
	s_and_b64 vcc, vcc, s[10:11]
	v_add_u32_e32 v65, 25, v139
	v_cndmask_b32_e32 v171, v197, v76, vcc
	v_cmp_le_i32_e32 vcc, v65, v128
	v_add_u32_e32 v65, 2, v134
	v_cmp_gt_i32_e64 s[10:11], s65, v65
	s_and_b64 vcc, vcc, s[10:11]
	v_add_u32_e32 v65, 26, v139
	v_max3_f32 v64, v64, v141, v142
	v_cndmask_b32_e32 v172, v197, v77, vcc
	v_cmp_le_i32_e32 vcc, v65, v128
	v_add_u32_e32 v65, 1, v134
	v_max3_f32 v64, v64, v143, v144
	v_cmp_gt_i32_e64 s[10:11], s65, v65
	v_max3_f32 v64, v64, v145, v146
	s_and_b64 vcc, vcc, s[10:11]
	v_add_u32_e32 v65, 27, v139
	v_max3_f32 v64, v64, v147, v150
	v_cndmask_b32_e32 v173, v197, v78, vcc
	v_cmp_le_i32_e32 vcc, v65, v128
	v_cmp_gt_i32_e64 s[10:11], s65, v134
	v_max3_f32 v64, v64, v168, v170
	s_and_b64 vcc, vcc, s[10:11]
	v_max3_f32 v64, v64, v171, v172
	v_cndmask_b32_e32 v139, v197, v79, vcc
	v_max3_f32 v64, v64, v173, v139
	v_mov_b32_e32 v65, v64
	s_nop 1
	v_permlane32_swap_b32_e32 v65, v64
	v_cmp_lt_f32_e32 vcc, s33, v138
	v_max3_f32 v65, v137, v64, v65
	v_sub_f32_e32 v66, v138, v65
	v_exp_f32_e32 v66, v66
	v_sub_f32_e32 v67, v140, v65
	v_exp_f32_e32 v67, v67
	v_sub_f32_e32 v68, v141, v65
	v_exp_f32_e32 v68, v68
	v_sub_f32_e32 v69, v142, v65
	v_exp_f32_e32 v69, v69
	v_sub_f32_e32 v70, v143, v65
	v_cndmask_b32_e32 v66, 0, v66, vcc
	v_cmp_lt_f32_e32 vcc, s33, v140
	v_exp_f32_e32 v70, v70
	v_sub_f32_e32 v71, v144, v65
	v_cndmask_b32_e32 v67, 0, v67, vcc
	v_cmp_lt_f32_e32 vcc, s33, v141
	v_exp_f32_e32 v71, v71
	v_sub_f32_e32 v72, v145, v65
	v_cndmask_b32_e32 v68, 0, v68, vcc
	v_cmp_lt_f32_e32 vcc, s33, v142
; #define MFMA32(a, b, c) __builtin_amdgcn_mfma_f32_32x32x16_bf16((a), (b), (c), 0, 0, 0)
; template <int MODE>
; DI void attn_item(const u16* __restrict__ Qp, const u16* __restrict__ Kp, const u16* __restrict__ VTp, int q0,
;                   int kt_lo, int kt_hi, u16* __restrict__ Op, int os, float* __restrict__ lsep, int ls, char* lds, int tid) {
;     ...
;       const float m_new = fmaxf(m_run, mx);
;       const float alpha = __builtin_amdgcn_exp2f(m_run - m_new);
;       m_run = m_new;
;       float psum = 0.f;
; #pragma unroll
;       for (int mt = 0; mt < NMT; mt++)
; #pragma unroll
;         for (int r = 0; r < 16; r++) {
;           const float s = st[mt][r];
;           const float p = (s > -1e29f) ? __builtin_amdgcn_exp2f(s - m_new) : 0.f;
;           psum += p;
;           st[mt][r] = p;
;         }
;       l_run = l_run * alpha + psum;
; #pragma unroll
;       for (int d = 0; d < 4; d++)
; #pragma unroll
;         for (int r = 0; r < 16; r++) ot[d][r] *= alpha;
;     ...
; #pragma unroll
;     for (int s4 = 0; s4 < NS4; s4++) {
;       const int mt = s4 >> 1, r0 = (s4 & 1) * 8;
;       uint4 pw;
;       pw.x = pack2(st[mt][r0 + 0], st[mt][r0 + 1]);
;       pw.y = pack2(st[mt][r0 + 2], st[mt][r0 + 3]);
;       pw.z = pack2(st[mt][r0 + 4], st[mt][r0 + 5]);
;       pw.w = pack2(st[mt][r0 + 6], st[mt][r0 + 7]);
;       const bf16x8 pb = __builtin_bit_cast(bf16x8, pw);
; #pragma unroll
;       for (int dt = 0; dt < 4; dt++) {
;         const char* vr = Vs + (dt * 32 + c) * VROW + (16 * s4 + 4 * h) * 2;
;         const bf16x4 lo = *(const bf16x4*)(vr);
;         const bf16x4 hi = *(const bf16x4*)(vr + 16);
;         const bf16x8 vf = __builtin_shufflevector(lo, hi, 0, 1, 2, 3, 4, 5, 6, 7);
;         ot[dt] = MFMA32(vf, pb, ot[dt]);
;       }
;     }
;     if (MODE == 1) {
;       if (__syncthreads_and(R < -100.f)) break;
;     }
;     if (PF) {
;       if (it + 1 < ntiles) { PF_STORE((it + 1) & 1) }
	v_exp_f32_e32 v72, v72
	v_sub_f32_e32 v73, v146, v65
	v_cndmask_b32_e32 v69, 0, v69, vcc
	v_cmp_lt_f32_e32 vcc, s33, v143
	v_exp_f32_e32 v73, v73
	v_sub_f32_e32 v74, v147, v65
	v_cndmask_b32_e32 v70, 0, v70, vcc
	v_cmp_lt_f32_e32 vcc, s33, v144
	v_exp_f32_e32 v74, v74
	v_sub_f32_e32 v75, v150, v65
	v_cndmask_b32_e32 v71, 0, v71, vcc
	v_cmp_lt_f32_e32 vcc, s33, v145
	v_exp_f32_e32 v75, v75
	v_sub_f32_e32 v76, v168, v65
	v_cndmask_b32_e32 v72, 0, v72, vcc
	v_cmp_lt_f32_e32 vcc, s33, v146
	v_exp_f32_e32 v76, v76
	v_sub_f32_e32 v77, v170, v65
	v_cndmask_b32_e32 v73, 0, v73, vcc
	v_cmp_lt_f32_e32 vcc, s33, v147
	v_exp_f32_e32 v77, v77
	v_sub_f32_e32 v78, v171, v65
	v_cndmask_b32_e32 v74, 0, v74, vcc
	v_cmp_lt_f32_e32 vcc, s33, v150
	v_exp_f32_e32 v78, v78
	v_sub_f32_e32 v79, v172, v65
	v_sub_f32_e32 v64, v137, v65
	v_cndmask_b32_e32 v75, 0, v75, vcc
	v_cmp_lt_f32_e32 vcc, s33, v168
	v_exp_f32_e32 v79, v79
	v_sub_f32_e32 v137, v173, v65
	v_cndmask_b32_e32 v76, 0, v76, vcc
	v_cmp_lt_f32_e32 vcc, s33, v170
	v_exp_f32_e32 v137, v137
	v_sub_f32_e32 v138, v139, v65
	v_cndmask_b32_e32 v77, 0, v77, vcc
	v_cmp_lt_f32_e32 vcc, s33, v171
	v_exp_f32_e32 v64, v64
	v_cvt_pk_bf16_f32 v140, v66, v67
	v_cndmask_b32_e32 v78, 0, v78, vcc
	v_cmp_lt_f32_e32 vcc, s33, v172
	v_pk_mul_f32 v[62:63], v[62:63], v[64:65] op_sel_hi:[1,0]
	v_pk_mul_f32 v[60:61], v[60:61], v[64:65] op_sel_hi:[1,0]
	v_cndmask_b32_e32 v79, 0, v79, vcc
	v_cmp_lt_f32_e32 vcc, s33, v173
	v_pk_mul_f32 v[58:59], v[58:59], v[64:65] op_sel_hi:[1,0]
	v_pk_mul_f32 v[56:57], v[56:57], v[64:65] op_sel_hi:[1,0]
	v_cndmask_b32_e32 v137, 0, v137, vcc
	v_cmp_lt_f32_e32 vcc, s33, v139
	v_or_b32_e32 v139, s39, v156
	v_add_u32_e32 v139, v139, v208
	v_add_u32_e32 v150, 0x2000, v139
	ds_read2_b64 v[144:147], v150 offset0:64 offset1:66
	v_pk_mul_f32 v[54:55], v[54:55], v[64:65] op_sel_hi:[1,0]
	v_pk_mul_f32 v[52:53], v[52:53], v[64:65] op_sel_hi:[1,0]
	v_pk_mul_f32 v[50:51], v[50:51], v[64:65] op_sel_hi:[1,0]
	v_pk_mul_f32 v[48:49], v[48:49], v[64:65] op_sel_hi:[1,0]
	v_cvt_pk_bf16_f32 v141, v68, v69
	v_cvt_pk_bf16_f32 v142, v70, v71
	v_cvt_pk_bf16_f32 v143, v72, v73
	ds_read2_b64 v[170:173], v150 offset0:68 offset1:70
	v_add_u32_e32 v150, 0x2800, v139
	s_setprio 1
	s_waitcnt lgkmcnt(1)
	v_mfma_f32_32x32x16_bf16 v[48:63], v[144:147], v[140:143], v[48:63]
	ds_read2_b64 v[144:147], v150 offset0:128 offset1:130
	v_mul_f32_e64 v46, v46, v64
	v_mul_f32_e64 v47, v47, v64
	v_mul_f32_e64 v44, v44, v64
	v_mul_f32_e64 v45, v45, v64
	v_pk_mul_f32 v[42:43], v[42:43], v[64:65] op_sel_hi:[1,0]
	v_pk_mul_f32 v[40:41], v[40:41], v[64:65] op_sel_hi:[1,0]
	v_pk_mul_f32 v[38:39], v[38:39], v[64:65] op_sel_hi:[1,0]
	v_pk_mul_f32 v[36:37], v[36:37], v[64:65] op_sel_hi:[1,0]
	v_pk_mul_f32 v[34:35], v[34:35], v[64:65] op_sel_hi:[1,0]
	v_pk_mul_f32 v[32:33], v[32:33], v[64:65] op_sel_hi:[1,0]
	v_add_u32_e32 v168, 0x3000, v139
	v_pk_mul_f32 v[30:31], v[30:31], v[64:65] op_sel_hi:[1,0]
	s_waitcnt lgkmcnt(0)
	v_mfma_f32_32x32x16_bf16 v[32:47], v[144:147], v[140:143], v[32:47]
	ds_read2_b64 v[144:147], v168 offset0:192 offset1:194
	v_mul_f32_e64 v28, v28, v64
	v_mul_f32_e64 v29, v29, v64
	v_mul_f32_e64 v26, v26, v64
	v_mul_f32_e64 v27, v27, v64
	v_pk_mul_f32 v[24:25], v[24:25], v[64:65] op_sel_hi:[1,0]
	v_pk_mul_f32 v[22:23], v[22:23], v[64:65] op_sel_hi:[1,0]
	v_pk_mul_f32 v[20:21], v[20:21], v[64:65] op_sel_hi:[1,0]
	v_pk_mul_f32 v[18:19], v[18:19], v[64:65] op_sel_hi:[1,0]
	v_pk_mul_f32 v[16:17], v[16:17], v[64:65] op_sel_hi:[1,0]
	v_add_u32_e32 v139, 0x4000, v139
	v_pk_mul_f32 v[14:15], v[14:15], v[64:65] op_sel_hi:[1,0]
	s_waitcnt lgkmcnt(0)
	v_mfma_f32_32x32x16_bf16 v[16:31], v[144:147], v[140:143], v[16:31]
	ds_read2_b64 v[144:147], v139 offset1:2
	v_mul_f32_e64 v12, v12, v64
	v_mul_f32_e64 v13, v13, v64
	v_mul_f32_e64 v10, v10, v64
	v_mul_f32_e64 v11, v11, v64
	v_pk_mul_f32 v[8:9], v[8:9], v[64:65] op_sel_hi:[1,0]
	v_pk_mul_f32 v[6:7], v[6:7], v[64:65] op_sel_hi:[1,0]
	v_pk_mul_f32 v[4:5], v[4:5], v[64:65] op_sel_hi:[1,0]
	v_pk_mul_f32 v[2:3], v[2:3], v[64:65] op_sel_hi:[1,0]
	v_pk_mul_f32 v[0:1], v[0:1], v[64:65] op_sel_hi:[1,0]
	v_exp_f32_e32 v138, v138
	s_waitcnt lgkmcnt(0)
	v_mfma_f32_32x32x16_bf16 v[0:15], v[144:147], v[140:143], v[0:15]
	ds_read2_b64 v[144:147], v150 offset0:132 offset1:134
	v_cndmask_b32_e32 v138, 0, v138, vcc
	v_cvt_pk_bf16_f32 v140, v74, v75
	v_cvt_pk_bf16_f32 v141, v76, v77
	v_cvt_pk_bf16_f32 v142, v78, v79
	v_cvt_pk_bf16_f32 v143, v137, v138
	s_andn2_b64 vcc, exec, s[42:43]
	s_waitcnt lgkmcnt(0)
	v_mfma_f32_32x32x16_bf16 v[32:47], v[144:147], v[140:143], v[32:47]
	ds_read2_b64 v[144:147], v168 offset0:196 offset1:198
	s_waitcnt lgkmcnt(0)
	v_mfma_f32_32x32x16_bf16 v[16:31], v[144:147], v[140:143], v[16:31]
	ds_read2_b64 v[144:147], v139 offset0:4 offset1:6
	v_mfma_f32_32x32x16_bf16 v[48:63], v[170:173], v[140:143], v[48:63]
	s_waitcnt lgkmcnt(0)
	v_mfma_f32_32x32x16_bf16 v[0:15], v[144:147], v[140:143], v[0:15]
	s_setprio 0
	s_cbranch_vccnz .LBB0_441
	s_bitcmp1_b32 s49, 0
	s_cselect_b32 s10, 0x4a00, 0
	v_add3_u32 v139, s10, v176, v174
	v_add3_u32 v140, s10, v177, v175
	s_waitcnt vmcnt(3)
	ds_write_b128 v139, v[112:115]
	s_waitcnt vmcnt(1)
	ds_write_b128 v139, v[116:119] offset:128
	ds_write_b128 v140, v[120:123] offset:8704
	s_waitcnt vmcnt(0)
	ds_write_b128 v140, v[124:127] offset:13824

; template <int MODE>
; DI void attn_item(const u16* __restrict__ Qp, const u16* __restrict__ Kp, const u16* __restrict__ VTp, int q0,
;                   int kt_lo, int kt_hi, u16* __restrict__ Op, int os, float* __restrict__ lsep, int ls, char* lds, int tid) {
;     ...
; #pragma unroll 1
;   for (int it = 0; it < ntiles; it++) {
;     const int kt = (MODE == 1) ? (kt_hi - it) : (kt_lo + it);
;     char* Ks = lds + (PF ? (it & 1) * STAGE : 0);
;     char* Vs = Ks + KT * KROW;
;     if (PF) {
;       if (it + 1 < ntiles) { PF_LOAD(kt + 1) }
.LBB0_473:
	v_mov_b32_e32 v64, v235
	s_add_i32 s10, s10, 32
	v_fmac_f32_e32 v64, v150, v68
	s_cmp_lg_u32 s46, s42
	s_waitcnt lgkmcnt(0)
	s_barrier
	s_cbranch_scc0 .LBB0_426
	v_mov_b32_e32 v150, v64
	v_mov_b32_e32 v218, v217
	s_cmp_lt_u32 s42, s43
	s_cselect_b64 s[12:13], -1, 0
	s_cmp_ge_u32 s42, s43
	s_cbranch_scc1 .LBB0_467
	s_branch .LBB0_466
